# mlstm_a gate scans: DPP row_shr/row_bcast scans and v_readlane broadcasts instead of 28 dependent ds_bpermute round trips (wave 0 serial section)
# speedup vs baseline: 1.0026x; 1.0026x over previous
.LBB0_369:
	s_and_b32 s18, s65, 0x1c0
	s_and_b32 s19, s73, 0xfffffe00
	s_or_b32 s41, s18, s19
	s_bfe_u32 s26, s73, 0x60003
	v_cndmask_b32_e64 v0, 0, 1, s[30:31]
	s_or_b32 s40, s41, s26
	v_cmp_ne_u32_e64 s[18:19], 1, v0
	s_andn2_b64 vcc, exec, s[30:31]
	s_waitcnt vmcnt(0) lgkmcnt(0)
	s_barrier
	s_cbranch_vccnz .LBB0_373
	s_lshr_b32 s42, s41, 4
	s_and_b32 s42, s42, 28
	v_mov_b32_e32 v0, s42
	global_load_dword v1, v0, s[28:29] offset:32
	global_load_dword v4, v0, s[28:29]
	s_ashr_i32 s42, s41, 6
	s_ashr_i32 s43, s42, 31
	s_lshl_b64 s[42:43], s[42:43], 15
	s_waitcnt vmcnt(1)
	v_add_f32_e32 v0, v59, v1
	v_mul_f32_e64 v2, |v0|, s67
	v_add_f32_e32 v1, v58, v1
	v_exp_f32_e32 v5, v2
	v_mul_f32_e64 v3, |v1|, s67
	v_exp_f32_e32 v6, v3
	v_min_f32_e32 v7, 0, v0
	v_add_f32_e32 v9, 1.0, v5
	v_min_f32_e32 v8, 0, v1
	v_frexp_mant_f32_e32 v12, v9
	v_cvt_f64_f32_e32 v[0:1], v9
	v_add_f32_e32 v10, 1.0, v6
	v_add_f32_e32 v11, -1.0, v9
	v_frexp_exp_i32_f64_e32 v0, v[0:1]
	v_cmp_gt_f32_e32 vcc, s68, v12
	v_add_f32_e32 v13, -1.0, v10
	v_frexp_mant_f32_e32 v14, v10
	v_cvt_f64_f32_e32 v[2:3], v10
	v_sub_f32_e32 v15, v11, v9
	v_subbrev_co_u32_e32 v0, vcc, 0, v0, vcc
	v_sub_f32_e32 v11, v5, v11
	v_sub_f32_e32 v1, v13, v10
	v_frexp_exp_i32_f64_e32 v2, v[2:3]
	v_add_f32_e32 v3, 1.0, v15
	v_cmp_gt_f32_e32 vcc, s68, v14
	v_sub_f32_e32 v13, v6, v13
	v_add_f32_e32 v1, 1.0, v1
	v_subbrev_co_u32_e32 v2, vcc, 0, v2, vcc
	v_add_f32_e32 v3, v11, v3
	v_sub_u32_e32 v11, 0, v0
	v_add_f32_e32 v1, v13, v1
	v_sub_u32_e32 v12, 0, v2
	v_ldexp_f32 v9, v9, v11
	v_cvt_f32_i32_e32 v0, v0
	v_ldexp_f32 v3, v3, v11
	v_ldexp_f32 v10, v10, v12
	v_ldexp_f32 v1, v1, v12
	v_add_f32_e32 v11, -1.0, v9
	v_add_f32_e32 v12, 1.0, v9
	v_add_f32_e32 v15, 1.0, v11
	v_add_f32_e32 v76, -1.0, v12
	v_add_f32_e32 v13, -1.0, v10
	v_add_f32_e32 v14, 1.0, v10
	v_sub_f32_e32 v15, v9, v15
	v_sub_f32_e32 v9, v9, v76
	v_add_f32_e32 v77, 1.0, v13
	v_add_f32_e32 v78, -1.0, v14
	v_add_f32_e32 v15, v3, v15
	v_add_f32_e32 v3, v3, v9
	v_mul_f32_e32 v76, 0x3f317218, v0
	v_sub_f32_e32 v77, v10, v77
	v_sub_f32_e32 v10, v10, v78
	v_add_f32_e32 v78, v12, v3
	v_fma_f32 v9, v0, s69, -v76
	v_rcp_f32_e32 v80, v78
	v_fmac_f32_e32 v9, 0xb102e308, v0
	v_sub_f32_e32 v12, v78, v12
	v_add_f32_e32 v81, v76, v9
	v_add_f32_e32 v77, v1, v77
	v_add_f32_e32 v1, v1, v10
	v_add_f32_e32 v10, v11, v15
	v_sub_f32_e32 v3, v3, v12
	v_sub_f32_e32 v12, v81, v76
	v_sub_f32_e32 v11, v10, v11
	v_sub_f32_e32 v9, v9, v12
	v_mul_f32_e32 v12, v10, v80
	v_sub_f32_e32 v11, v15, v11
	v_mul_f32_e32 v15, v78, v12
	v_fma_f32 v76, v12, v78, -v15
	v_fmac_f32_e32 v76, v12, v3
	v_add_f32_e32 v83, v15, v76
	v_sub_f32_e32 v84, v10, v83
	v_sub_f32_e32 v10, v10, v84
	v_sub_f32_e32 v15, v83, v15
	v_sub_f32_e32 v10, v10, v83
	v_sub_f32_e32 v15, v15, v76
	v_add_f32_e32 v10, v11, v10
	v_add_f32_e32 v10, v15, v10
	v_add_f32_e32 v11, v84, v10
	v_mul_f32_e32 v15, v80, v11
	v_sub_f32_e32 v76, v84, v11
	v_mul_f32_e32 v83, v78, v15
	v_add_f32_e32 v10, v10, v76
	v_add_f32_e32 v76, v12, v15
	v_fma_f32 v78, v15, v78, -v83
	v_sub_f32_e32 v12, v76, v12
	v_fmac_f32_e32 v78, v15, v3
	v_sub_f32_e32 v3, v15, v12
	v_add_f32_e32 v12, v83, v78
	v_sub_f32_e32 v15, v12, v83
	v_sub_f32_e32 v83, v11, v12
	v_sub_f32_e32 v11, v11, v83
	v_sub_f32_e32 v11, v11, v12
	v_sub_f32_e32 v15, v15, v78
	v_add_f32_e32 v10, v10, v11
	v_add_f32_e32 v10, v15, v10
	v_add_f32_e32 v10, v83, v10
	v_mul_f32_e32 v10, v80, v10
	v_add_f32_e32 v3, v3, v10
	v_add_f32_e32 v10, v76, v3
	v_mul_f32_e32 v11, v10, v10
	v_sub_f32_e32 v12, v10, v76
	v_fmamk_f32 v76, v11, 0x3e9b6dac, v42
	v_ldexp_f32 v15, v10, 1
	v_mul_f32_e32 v10, v10, v11
	v_fmaak_f32 v11, v11, v76, 0x3f2aaada
	v_mul_f32_e32 v10, v10, v11
	v_add_f32_e32 v11, v15, v10
	v_sub_f32_e32 v3, v3, v12
	v_sub_f32_e32 v12, v11, v15
	v_ldexp_f32 v3, v3, 1
	v_sub_f32_e32 v10, v10, v12
	v_add_f32_e32 v3, v3, v10
	v_add_f32_e32 v10, v11, v3
	v_sub_f32_e32 v11, v10, v11
	v_add_f32_e32 v12, v81, v10
	v_sub_f32_e32 v3, v3, v11
	v_sub_f32_e32 v11, v12, v81
	v_sub_f32_e32 v15, v12, v11
	v_sub_f32_e32 v10, v10, v11
	v_add_f32_e32 v11, v9, v3
	v_sub_f32_e32 v15, v81, v15
	v_sub_f32_e32 v76, v11, v9
	v_add_f32_e32 v10, v10, v15
	v_sub_f32_e32 v15, v11, v76
	v_sub_f32_e32 v3, v3, v76
	v_sub_f32_e32 v9, v9, v15
	v_add_f32_e32 v10, v11, v10
	v_add_f32_e32 v3, v3, v9
	v_add_f32_e32 v9, v12, v10
	v_sub_f32_e32 v11, v9, v12
	v_sub_f32_e32 v10, v10, v11
	v_add_f32_e32 v3, v3, v10
	v_add_f32_e32 v3, v9, v3
	v_cmp_neq_f32_e32 vcc, s70, v5
	v_add_f32_e32 v79, v14, v1
	v_rcp_f32_e32 v82, v79
	v_cndmask_b32_e32 v3, v71, v3, vcc
	v_cmp_ngt_f32_e32 vcc, -1.0, v5
	v_add_f32_e32 v0, v13, v77
	v_sub_f32_e32 v13, v0, v13
	v_cndmask_b32_e32 v3, v72, v3, vcc
	v_cmp_neq_f32_e32 vcc, -1.0, v5
	v_cvt_f32_i32_e32 v2, v2
	s_nop 0
	v_cndmask_b32_e32 v3, v73, v3, vcc
	v_cmp_lt_f32_e64 vcc, |v5|, s71
	s_nop 1
	v_cndmask_b32_e32 v3, v3, v5, vcc
	v_sub_f32_e32 v3, v7, v3
	v_sub_f32_e32 v7, v79, v14
	v_sub_f32_e32 v1, v1, v7
	v_mul_f32_e32 v7, v0, v82
	v_mul_f32_e32 v9, v79, v7
	v_fma_f32 v10, v7, v79, -v9
	v_fmac_f32_e32 v10, v7, v1
	v_add_f32_e32 v11, v9, v10
	v_sub_f32_e32 v12, v0, v11
	v_sub_f32_e32 v0, v0, v12
	v_sub_f32_e32 v5, v77, v13
	v_sub_f32_e32 v9, v11, v9
	v_sub_f32_e32 v0, v0, v11
	v_add_f32_e32 v0, v5, v0
	v_sub_f32_e32 v5, v9, v10
	v_add_f32_e32 v0, v5, v0
	v_add_f32_e32 v5, v12, v0
	v_mul_f32_e32 v9, v82, v5
	v_mul_f32_e32 v10, v79, v9
	v_fma_f32 v11, v9, v79, -v10
	v_fmac_f32_e32 v11, v9, v1
	v_sub_f32_e32 v1, v12, v5
	v_add_f32_e32 v0, v0, v1
	v_add_f32_e32 v1, v10, v11
	v_sub_f32_e32 v12, v5, v1
	v_sub_f32_e32 v5, v5, v12
	v_sub_f32_e32 v10, v1, v10
	v_sub_f32_e32 v1, v5, v1
	v_add_f32_e32 v0, v0, v1
	v_sub_f32_e32 v1, v10, v11
	v_add_f32_e32 v0, v1, v0
	v_add_f32_e32 v1, v7, v9
	v_add_f32_e32 v0, v12, v0
	v_sub_f32_e32 v5, v1, v7
	v_mul_f32_e32 v0, v82, v0
	v_sub_f32_e32 v5, v9, v5
	v_add_f32_e32 v0, v5, v0
	v_mul_f32_e32 v10, 0x3f317218, v2
	v_add_f32_e32 v5, v1, v0
	v_fma_f32 v11, v2, s69, -v10
	v_mul_f32_e32 v7, v5, v5
	v_fmac_f32_e32 v11, 0xb102e308, v2
	v_sub_f32_e32 v1, v5, v1
	v_fmamk_f32 v9, v7, 0x3e9b6dac, v42
	v_sub_f32_e32 v0, v0, v1
	v_add_f32_e32 v1, v10, v11
	v_fmaak_f32 v9, v7, v9, 0x3f2aaada
	v_sub_f32_e32 v2, v1, v10
	v_ldexp_f32 v10, v5, 1
	v_mul_f32_e32 v5, v5, v7
	v_mul_f32_e32 v5, v5, v9
	v_add_f32_e32 v7, v10, v5
	v_sub_f32_e32 v9, v7, v10
	v_ldexp_f32 v0, v0, 1
	v_sub_f32_e32 v5, v5, v9
	v_add_f32_e32 v0, v0, v5
	v_add_f32_e32 v5, v7, v0
	v_sub_f32_e32 v7, v5, v7
	v_sub_f32_e32 v0, v0, v7
	v_add_f32_e32 v7, v1, v5
	v_sub_f32_e32 v9, v7, v1
	v_sub_f32_e32 v10, v7, v9
	v_sub_f32_e32 v2, v11, v2
	v_sub_f32_e32 v1, v1, v10
	v_sub_f32_e32 v5, v5, v9
	v_add_f32_e32 v1, v5, v1
	v_add_f32_e32 v5, v2, v0
	v_sub_f32_e32 v9, v5, v2
	v_sub_f32_e32 v10, v5, v9
	v_sub_f32_e32 v2, v2, v10
	v_sub_f32_e32 v0, v0, v9
	v_add_f32_e32 v1, v5, v1
	v_add_f32_e32 v0, v0, v2
	v_add_f32_e32 v2, v7, v1
	v_sub_f32_e32 v5, v2, v7
	v_sub_f32_e32 v1, v1, v5
	v_add_f32_e32 v0, v0, v1
	v_add_f32_e32 v0, v2, v0
	v_cmp_neq_f32_e32 vcc, s70, v6
	v_and_b32_e32 v1, 64, v74
	v_add_u32_e32 v2, -1, v74
	v_cndmask_b32_e32 v0, v71, v0, vcc
	v_cmp_ngt_f32_e32 vcc, -1.0, v6
	s_nop 1
	v_cndmask_b32_e32 v0, v72, v0, vcc
	v_cmp_neq_f32_e32 vcc, -1.0, v6
	s_nop 1
	v_cndmask_b32_e32 v0, v73, v0, vcc
	v_cmp_lt_f32_e64 vcc, |v6|, s71
	s_nop 1
	v_cndmask_b32_e32 v0, v0, v6, vcc
	v_sub_f32_e32 v0, v8, v0
	s_nop 1
	v_add_f32_dpp v3, v3, v3 row_shr:1 row_mask:0xf bank_mask:0xf
	v_add_f32_dpp v0, v0, v0 row_shr:1 row_mask:0xf bank_mask:0xf
	s_nop 0
	v_add_f32_dpp v3, v3, v3 row_shr:2 row_mask:0xf bank_mask:0xf
	v_add_f32_dpp v0, v0, v0 row_shr:2 row_mask:0xf bank_mask:0xf
	s_nop 0
	v_add_f32_dpp v3, v3, v3 row_shr:4 row_mask:0xf bank_mask:0xf
	v_add_f32_dpp v0, v0, v0 row_shr:4 row_mask:0xf bank_mask:0xf
	s_nop 0
	v_add_f32_dpp v3, v3, v3 row_shr:8 row_mask:0xf bank_mask:0xf
	v_add_f32_dpp v0, v0, v0 row_shr:8 row_mask:0xf bank_mask:0xf
	s_nop 0
	v_add_f32_dpp v3, v3, v3 row_bcast:15 row_mask:0xa bank_mask:0xf
	v_add_f32_dpp v0, v0, v0 row_bcast:15 row_mask:0xa bank_mask:0xf
	s_nop 0
	v_add_f32_dpp v3, v3, v3 row_bcast:31 row_mask:0xc bank_mask:0xf
	v_add_f32_dpp v0, v0, v0 row_bcast:31 row_mask:0xc bank_mask:0xf
	s_nop 0
	s_nop 0
	v_mov_b32_e32 v10, v3
	v_readlane_b32 s54, v3, 63
	s_waitcnt vmcnt(0)
	v_add_f32_e32 v6, v56, v4
	v_add_f32_e32 v4, v57, v4
	v_add_f32_e32 v11, s54, v0
	v_sub_f32_e32 v6, v6, v10
	v_sub_f32_e32 v12, v4, v11
	ds_write2st64_b32 v60, v6, v12 offset1:1
	v_mov_b32_e32 v8, v6
	v_mov_b32_e32 v1, v12
	s_nop 1
	v_max_f32_dpp v8, v8, v8 row_shr:1 row_mask:0xf bank_mask:0xf
	v_max_f32_dpp v1, v1, v1 row_shr:1 row_mask:0xf bank_mask:0xf
	s_nop 0
	v_max_f32_dpp v8, v8, v8 row_shr:2 row_mask:0xf bank_mask:0xf
	v_max_f32_dpp v1, v1, v1 row_shr:2 row_mask:0xf bank_mask:0xf
	s_nop 0
	v_max_f32_dpp v8, v8, v8 row_shr:4 row_mask:0xf bank_mask:0xf
	v_max_f32_dpp v1, v1, v1 row_shr:4 row_mask:0xf bank_mask:0xf
	s_nop 0
	v_max_f32_dpp v8, v8, v8 row_shr:8 row_mask:0xf bank_mask:0xf
	v_max_f32_dpp v1, v1, v1 row_shr:8 row_mask:0xf bank_mask:0xf
	s_nop 0
	v_max_f32_dpp v8, v8, v8 row_bcast:15 row_mask:0xa bank_mask:0xf
	v_max_f32_dpp v1, v1, v1 row_bcast:15 row_mask:0xa bank_mask:0xf
	s_nop 0
	v_max_f32_dpp v8, v8, v8 row_bcast:31 row_mask:0xc bank_mask:0xf
	v_max_f32_dpp v1, v1, v1 row_bcast:31 row_mask:0xc bank_mask:0xf
	s_nop 0
	s_nop 0
	v_readlane_b32 s54, v8, 63
	v_readlane_b32 s60, v11, 63
	v_max_f32_e32 v9, s54, v1
	s_nop 1
	v_readlane_b32 s55, v9, 63
	v_mov_b32_e32 v1, s60
	v_mov_b32_e32 v0, s55
	v_sub_f32_e32 v2, v6, v0
	v_mul_f32_e32 v2, 0x3fb8aa3b, v2
	v_exp_f32_e32 v2, v2
	v_sub_f32_e32 v3, v12, v0
	v_mul_f32_e32 v3, 0x3fb8aa3b, v3
	v_exp_f32_e32 v3, v3
	s_nop 0
	v_mul_f32_e32 v2, 0x3e000000, v2
	v_mul_f32_e32 v3, 0x3e000000, v3
	ds_write2st64_b32 v60, v2, v3 offset0:2 offset1:3
	v_lshlrev_b32_e32 v2, 2, v54
	v_lshl_or_b32 v2, s26, 9, v2
	v_or_b32_e32 v2, s42, v2
	v_mov_b32_e32 v3, s43
	v_lshl_add_u64 v[4:5], s[34:35], 0, v[2:3]
	global_store_dword v[4:5], v6, off
	v_or_b32_e32 v4, 0x100, v2
	v_mov_b32_e32 v5, s43
	v_lshl_add_u64 v[6:7], s[34:35], 0, v[4:5]
	global_store_dword v[6:7], v12, off
	v_lshl_add_u64 v[6:7], s[36:37], 0, v[2:3]
	v_lshl_add_u64 v[2:3], s[38:39], 0, v[2:3]
	global_store_dword v[6:7], v10, off
	v_lshl_add_u64 v[6:7], s[36:37], 0, v[4:5]
	global_store_dword v[2:3], v8, off
	v_lshl_add_u64 v[2:3], s[38:39], 0, v[4:5]
	global_store_dword v[6:7], v11, off
	global_store_dword v[2:3], v9, off
	s_and_saveexec_b64 s[42:43], s[4:5]
	s_cbranch_execz .LBB0_372
	s_ashr_i32 s41, s40, 31
	s_lshl_b64 s[54:55], s[40:41], 2
	s_add_u32 s60, s33, s54
	s_addc_u32 s61, s52, s55
	s_add_u32 s54, s53, s54
	s_addc_u32 s55, s62, s55
	global_store_dword v43, v0, s[60:61]
	s_waitcnt lgkmcnt(1)
	global_store_dword v43, v1, s[54:55]
